# G3 SwiGLU epilogue: same f32 operations issued as packed pairs (v_pk_mul_f32/v_pk_add_f32), exp and rcp unchanged, bit-identical; stacked on stack16
# baseline (speedup 1.0000x reference)
; __device__ __forceinline__ unsigned cvt_pk_bf16(float lo, float hi) { unsigned r; asm volatile("v_cvt_pk_bf16_f32 %0, %1, %2" : "=v"(r) : "v"(lo), "v"(hi)); return r; }
; #define x (arg_in(0))
; __device__ __forceinline__ float silu_mul(float g, float u) { return g * u * __builtin_amdgcn_rcpf(1.f + __builtin_amdgcn_exp2f(-1.4426950408889634f * g)); }
;     __device__ __forceinline__ void operator()(const f32x4 (&acc)[2][2][4][2], const Unit& u, int wr, int wc, int fr, int fq) const {
;         const int row0 = u.pm * BM + wr * 64 + fr, col0 = u.pn * HALF + wc * 32 + 8 * fq;
; #pragma unroll
;         for (int ai = 0; ai < 2; ++ai)
; #pragma unroll
;             for (int m = 0; m < 4; ++m) { bf16_t* rowp = O + (size_t)(row0 + ai * HALF + m * 16) * ldc + col0;
;                 const f32x4 g0 = acc[ai][0][m][0], g1 = acc[ai][0][m][1], u0 = acc[ai][1][m][0], u1 = acc[ai][1][m][1];
;                 u32x4 w; w.x = cvt_pk_bf16(silu_mul(g0[0], u0[0]), silu_mul(g0[1], u0[1])); w.y = cvt_pk_bf16(silu_mul(g0[2], u0[2]), silu_mul(g0[3], u0[3]));
;                 w.z = cvt_pk_bf16(silu_mul(g1[0], u1[0]), silu_mul(g1[1], u1[1])); w.w = cvt_pk_bf16(silu_mul(g1[2], u1[2]), silu_mul(g1[3], u1[3]));
;                 *(u32x4*)rowp = w; }
.LBB0_816:
	s_mov_b32 s98, 0xbfb8aa3b
	s_mov_b32 s99, 1.0
	v_pk_mul_f32 v[120:121], v[124:125], v[120:121]
	v_pk_mul_f32 v[122:123], v[126:127], v[122:123]
	v_pk_mul_f32 v[112:113], v[116:117], v[112:113]
	v_pk_mul_f32 v[114:115], v[118:119], v[114:115]
	v_pk_mul_f32 v[124:125], v[124:125], s[98:99] op_sel_hi:[1,0]
	v_pk_mul_f32 v[126:127], v[126:127], s[98:99] op_sel_hi:[1,0]
	v_pk_mul_f32 v[116:117], v[116:117], s[98:99] op_sel_hi:[1,0]
	v_pk_mul_f32 v[118:119], v[118:119], s[98:99] op_sel_hi:[1,0]
	v_exp_f32_e32 v124, v124
	v_exp_f32_e32 v125, v125
	v_exp_f32_e32 v126, v126
	v_exp_f32_e32 v127, v127
	v_exp_f32_e32 v116, v116
	v_exp_f32_e32 v117, v117
	v_exp_f32_e32 v118, v118
	v_exp_f32_e32 v119, v119
	v_pk_add_f32 v[124:125], v[124:125], s[98:99] op_sel:[0,1]
	v_pk_add_f32 v[126:127], v[126:127], s[98:99] op_sel:[0,1]
	v_pk_add_f32 v[116:117], v[116:117], s[98:99] op_sel:[0,1]
	v_pk_add_f32 v[118:119], v[118:119], s[98:99] op_sel:[0,1]
	v_rcp_f32_e32 v124, v124
	v_rcp_f32_e32 v125, v125
	v_rcp_f32_e32 v126, v126
	v_rcp_f32_e32 v127, v127
	v_rcp_f32_e32 v116, v116
	v_rcp_f32_e32 v117, v117
	v_rcp_f32_e32 v118, v118
	v_rcp_f32_e32 v119, v119
	v_pk_mul_f32 v[120:121], v[124:125], v[120:121]
	v_pk_mul_f32 v[122:123], v[126:127], v[122:123]
	v_pk_mul_f32 v[112:113], v[116:117], v[112:113]
	v_pk_mul_f32 v[114:115], v[118:119], v[114:115]
	v_lshl_or_b32 v142, s26, 7, v146
	v_lshl_add_u32 v148, s27, 8, v144
	v_ashrrev_i32_e32 v143, 31, v142
	v_mov_b64_e32 v[140:141], s[44:45]
	v_mad_i64_i32 v[150:151], s[26:27], v148, s11, v[140:141]
	v_lshlrev_b64 v[142:143], 1, v[142:143]
	v_lshl_add_u64 v[150:151], v[150:151], 0, v[142:143]
	v_cvt_pk_bf16_f32 v120, v120, v121
	v_cvt_pk_bf16_f32 v121, v122, v123
	v_cvt_pk_bf16_f32 v122, v112, v113
	v_cvt_pk_bf16_f32 v123, v114, v115
	global_store_dwordx4 v[150:151], v[120:123], off
	v_pk_mul_f32 v[104:105], v[108:109], v[104:105]
	v_pk_mul_f32 v[106:107], v[110:111], v[106:107]
	v_pk_mul_f32 v[96:97], v[100:101], v[96:97]
	v_pk_mul_f32 v[98:99], v[102:103], v[98:99]
	v_pk_mul_f32 v[108:109], v[108:109], s[98:99] op_sel_hi:[1,0]
	v_pk_mul_f32 v[110:111], v[110:111], s[98:99] op_sel_hi:[1,0]
	v_pk_mul_f32 v[100:101], v[100:101], s[98:99] op_sel_hi:[1,0]
	v_pk_mul_f32 v[102:103], v[102:103], s[98:99] op_sel_hi:[1,0]
	v_exp_f32_e32 v108, v108
	v_exp_f32_e32 v109, v109
	v_exp_f32_e32 v110, v110
	v_exp_f32_e32 v111, v111
	v_exp_f32_e32 v100, v100
	v_exp_f32_e32 v101, v101
	v_exp_f32_e32 v102, v102
	v_exp_f32_e32 v103, v103
	v_pk_add_f32 v[108:109], v[108:109], s[98:99] op_sel:[0,1]
	v_pk_add_f32 v[110:111], v[110:111], s[98:99] op_sel:[0,1]
	v_pk_add_f32 v[100:101], v[100:101], s[98:99] op_sel:[0,1]
	v_pk_add_f32 v[102:103], v[102:103], s[98:99] op_sel:[0,1]
	v_rcp_f32_e32 v108, v108
	v_rcp_f32_e32 v109, v109
	v_rcp_f32_e32 v110, v110
	v_rcp_f32_e32 v111, v111
	v_rcp_f32_e32 v100, v100
	v_rcp_f32_e32 v101, v101
	v_rcp_f32_e32 v102, v102
	v_rcp_f32_e32 v103, v103
	v_pk_mul_f32 v[104:105], v[108:109], v[104:105]
	v_pk_mul_f32 v[106:107], v[110:111], v[106:107]
	v_pk_mul_f32 v[96:97], v[100:101], v[96:97]
	v_pk_mul_f32 v[98:99], v[102:103], v[98:99]
	v_or_b32_e32 v112, 16, v148
	v_mad_i64_i32 v[112:113], s[26:27], v112, s11, v[140:141]
	v_lshl_add_u64 v[112:113], v[112:113], 0, v[142:143]
	v_cvt_pk_bf16_f32 v104, v104, v105
	v_cvt_pk_bf16_f32 v105, v106, v107
	v_cvt_pk_bf16_f32 v106, v96, v97
	v_cvt_pk_bf16_f32 v107, v98, v99
	global_store_dwordx4 v[112:113], v[104:107], off
	v_pk_mul_f32 v[88:89], v[92:93], v[88:89]
	v_pk_mul_f32 v[90:91], v[94:95], v[90:91]
	v_pk_mul_f32 v[80:81], v[84:85], v[80:81]
	v_pk_mul_f32 v[82:83], v[86:87], v[82:83]
	v_pk_mul_f32 v[92:93], v[92:93], s[98:99] op_sel_hi:[1,0]
	v_pk_mul_f32 v[94:95], v[94:95], s[98:99] op_sel_hi:[1,0]
	v_pk_mul_f32 v[84:85], v[84:85], s[98:99] op_sel_hi:[1,0]
	v_pk_mul_f32 v[86:87], v[86:87], s[98:99] op_sel_hi:[1,0]
	v_exp_f32_e32 v92, v92
	v_exp_f32_e32 v93, v93
	v_exp_f32_e32 v94, v94
	v_exp_f32_e32 v95, v95
	v_exp_f32_e32 v84, v84
	v_exp_f32_e32 v85, v85
	v_exp_f32_e32 v86, v86
	v_exp_f32_e32 v87, v87
	v_pk_add_f32 v[92:93], v[92:93], s[98:99] op_sel:[0,1]
	v_pk_add_f32 v[94:95], v[94:95], s[98:99] op_sel:[0,1]
	v_pk_add_f32 v[84:85], v[84:85], s[98:99] op_sel:[0,1]
	v_pk_add_f32 v[86:87], v[86:87], s[98:99] op_sel:[0,1]
	v_rcp_f32_e32 v92, v92
	v_rcp_f32_e32 v93, v93
	v_rcp_f32_e32 v94, v94
	v_rcp_f32_e32 v95, v95
	v_rcp_f32_e32 v84, v84
	v_rcp_f32_e32 v85, v85
	v_rcp_f32_e32 v86, v86
	v_rcp_f32_e32 v87, v87
	v_pk_mul_f32 v[88:89], v[92:93], v[88:89]
	v_pk_mul_f32 v[90:91], v[94:95], v[90:91]
	v_pk_mul_f32 v[80:81], v[84:85], v[80:81]
	v_pk_mul_f32 v[82:83], v[86:87], v[82:83]
	v_or_b32_e32 v96, 32, v148
	v_mad_i64_i32 v[96:97], s[26:27], v96, s11, v[140:141]
	v_lshl_add_u64 v[96:97], v[96:97], 0, v[142:143]
	v_cvt_pk_bf16_f32 v88, v88, v89
	v_cvt_pk_bf16_f32 v89, v90, v91
	v_cvt_pk_bf16_f32 v90, v80, v81
	v_cvt_pk_bf16_f32 v91, v82, v83
	global_store_dwordx4 v[96:97], v[88:91], off
	v_pk_mul_f32 v[72:73], v[76:77], v[72:73]
	v_pk_mul_f32 v[74:75], v[78:79], v[74:75]
	v_pk_mul_f32 v[64:65], v[68:69], v[64:65]
	v_pk_mul_f32 v[66:67], v[70:71], v[66:67]
	v_pk_mul_f32 v[76:77], v[76:77], s[98:99] op_sel_hi:[1,0]
	v_pk_mul_f32 v[78:79], v[78:79], s[98:99] op_sel_hi:[1,0]
	v_pk_mul_f32 v[68:69], v[68:69], s[98:99] op_sel_hi:[1,0]
	v_pk_mul_f32 v[70:71], v[70:71], s[98:99] op_sel_hi:[1,0]
	v_exp_f32_e32 v76, v76
	v_exp_f32_e32 v77, v77
	v_exp_f32_e32 v78, v78
	v_exp_f32_e32 v79, v79
	v_exp_f32_e32 v68, v68
	v_exp_f32_e32 v69, v69
	v_exp_f32_e32 v70, v70
	v_exp_f32_e32 v71, v71
	v_pk_add_f32 v[76:77], v[76:77], s[98:99] op_sel:[0,1]
; __device__ __forceinline__ unsigned cvt_pk_bf16(float lo, float hi) { unsigned r; asm volatile("v_cvt_pk_bf16_f32 %0, %1, %2" : "=v"(r) : "v"(lo), "v"(hi)); return r; }
; #define x (arg_in(0))
; __device__ __forceinline__ float silu_mul(float g, float u) { return g * u * __builtin_amdgcn_rcpf(1.f + __builtin_amdgcn_exp2f(-1.4426950408889634f * g)); }
;     __device__ __forceinline__ void operator()(const f32x4 (&acc)[2][2][4][2], const Unit& u, int wr, int wc, int fr, int fq) const {
;         const int row0 = u.pm * BM + wr * 64 + fr, col0 = u.pn * HALF + wc * 32 + 8 * fq;
; #pragma unroll
;         for (int ai = 0; ai < 2; ++ai)
; #pragma unroll
;             for (int m = 0; m < 4; ++m) { bf16_t* rowp = O + (size_t)(row0 + ai * HALF + m * 16) * ldc + col0;
;                 const f32x4 g0 = acc[ai][0][m][0], g1 = acc[ai][0][m][1], u0 = acc[ai][1][m][0], u1 = acc[ai][1][m][1];
;                 u32x4 w; w.x = cvt_pk_bf16(silu_mul(g0[0], u0[0]), silu_mul(g0[1], u0[1])); w.y = cvt_pk_bf16(silu_mul(g0[2], u0[2]), silu_mul(g0[3], u0[3]));
;                 w.z = cvt_pk_bf16(silu_mul(g1[0], u1[0]), silu_mul(g1[1], u1[1])); w.w = cvt_pk_bf16(silu_mul(g1[2], u1[2]), silu_mul(g1[3], u1[3]));
;                 *(u32x4*)rowp = w; }
	v_pk_add_f32 v[78:79], v[78:79], s[98:99] op_sel:[0,1]
	v_pk_add_f32 v[68:69], v[68:69], s[98:99] op_sel:[0,1]
	v_pk_add_f32 v[70:71], v[70:71], s[98:99] op_sel:[0,1]
	v_rcp_f32_e32 v76, v76
	v_rcp_f32_e32 v77, v77
	v_rcp_f32_e32 v78, v78
	v_rcp_f32_e32 v79, v79
	v_rcp_f32_e32 v68, v68
	v_rcp_f32_e32 v69, v69
	v_rcp_f32_e32 v70, v70
	v_rcp_f32_e32 v71, v71
	v_pk_mul_f32 v[72:73], v[76:77], v[72:73]
	v_pk_mul_f32 v[74:75], v[78:79], v[74:75]
	v_pk_mul_f32 v[64:65], v[68:69], v[64:65]
	v_pk_mul_f32 v[66:67], v[70:71], v[66:67]
	v_or_b32_e32 v80, 48, v148
	v_mad_i64_i32 v[80:81], s[26:27], v80, s11, v[140:141]
	v_lshl_add_u64 v[80:81], v[80:81], 0, v[142:143]
	v_cvt_pk_bf16_f32 v72, v72, v73
	v_cvt_pk_bf16_f32 v73, v74, v75
	v_cvt_pk_bf16_f32 v74, v64, v65
	v_cvt_pk_bf16_f32 v75, v66, v67
	global_store_dwordx4 v[80:81], v[72:75], off
	v_pk_mul_f32 v[56:57], v[60:61], v[56:57]
	v_pk_mul_f32 v[58:59], v[62:63], v[58:59]
	v_pk_mul_f32 v[48:49], v[52:53], v[48:49]
	v_pk_mul_f32 v[50:51], v[54:55], v[50:51]
	v_pk_mul_f32 v[60:61], v[60:61], s[98:99] op_sel_hi:[1,0]
	v_pk_mul_f32 v[62:63], v[62:63], s[98:99] op_sel_hi:[1,0]
	v_pk_mul_f32 v[52:53], v[52:53], s[98:99] op_sel_hi:[1,0]
	v_pk_mul_f32 v[54:55], v[54:55], s[98:99] op_sel_hi:[1,0]
	v_exp_f32_e32 v60, v60
	v_exp_f32_e32 v61, v61
	v_exp_f32_e32 v62, v62
	v_exp_f32_e32 v63, v63
	v_exp_f32_e32 v52, v52
	v_exp_f32_e32 v53, v53
	v_exp_f32_e32 v54, v54
	v_exp_f32_e32 v55, v55
	v_pk_add_f32 v[60:61], v[60:61], s[98:99] op_sel:[0,1]
	v_pk_add_f32 v[62:63], v[62:63], s[98:99] op_sel:[0,1]
	v_pk_add_f32 v[52:53], v[52:53], s[98:99] op_sel:[0,1]
	v_pk_add_f32 v[54:55], v[54:55], s[98:99] op_sel:[0,1]
	v_rcp_f32_e32 v60, v60
	v_rcp_f32_e32 v61, v61
	v_rcp_f32_e32 v62, v62
	v_rcp_f32_e32 v63, v63
	v_rcp_f32_e32 v52, v52
	v_rcp_f32_e32 v53, v53
	v_rcp_f32_e32 v54, v54
	v_rcp_f32_e32 v55, v55
	v_pk_mul_f32 v[56:57], v[60:61], v[56:57]
	v_pk_mul_f32 v[58:59], v[62:63], v[58:59]
	v_pk_mul_f32 v[48:49], v[52:53], v[48:49]
	v_pk_mul_f32 v[50:51], v[54:55], v[50:51]
	v_add_u32_e32 v64, 0x80, v148
	v_mad_i64_i32 v[64:65], s[26:27], v64, s11, v[140:141]
	v_lshl_add_u64 v[64:65], v[64:65], 0, v[142:143]
	v_cvt_pk_bf16_f32 v56, v56, v57
	v_cvt_pk_bf16_f32 v57, v58, v59
	v_cvt_pk_bf16_f32 v58, v48, v49
	v_cvt_pk_bf16_f32 v59, v50, v51
	global_store_dwordx4 v[64:65], v[56:59], off
	v_pk_mul_f32 v[40:41], v[44:45], v[40:41]
	v_pk_mul_f32 v[42:43], v[46:47], v[42:43]
	v_pk_mul_f32 v[32:33], v[36:37], v[32:33]
	v_pk_mul_f32 v[34:35], v[38:39], v[34:35]
	v_pk_mul_f32 v[44:45], v[44:45], s[98:99] op_sel_hi:[1,0]
	v_pk_mul_f32 v[46:47], v[46:47], s[98:99] op_sel_hi:[1,0]
	v_pk_mul_f32 v[36:37], v[36:37], s[98:99] op_sel_hi:[1,0]
	v_pk_mul_f32 v[38:39], v[38:39], s[98:99] op_sel_hi:[1,0]
	v_exp_f32_e32 v44, v44
	v_exp_f32_e32 v45, v45
	v_exp_f32_e32 v46, v46
	v_exp_f32_e32 v47, v47
	v_exp_f32_e32 v36, v36
	v_exp_f32_e32 v37, v37
	v_exp_f32_e32 v38, v38
	v_exp_f32_e32 v39, v39
	v_pk_add_f32 v[44:45], v[44:45], s[98:99] op_sel:[0,1]
	v_pk_add_f32 v[46:47], v[46:47], s[98:99] op_sel:[0,1]
	v_pk_add_f32 v[36:37], v[36:37], s[98:99] op_sel:[0,1]
	v_pk_add_f32 v[38:39], v[38:39], s[98:99] op_sel:[0,1]
	v_rcp_f32_e32 v44, v44
	v_rcp_f32_e32 v45, v45
	v_rcp_f32_e32 v46, v46
	v_rcp_f32_e32 v47, v47
	v_rcp_f32_e32 v36, v36
	v_rcp_f32_e32 v37, v37
	v_rcp_f32_e32 v38, v38
	v_rcp_f32_e32 v39, v39
	v_pk_mul_f32 v[40:41], v[44:45], v[40:41]
	v_pk_mul_f32 v[42:43], v[46:47], v[42:43]
	v_pk_mul_f32 v[32:33], v[36:37], v[32:33]
	v_pk_mul_f32 v[34:35], v[38:39], v[34:35]
	v_add_u32_e32 v48, 0x90, v148
	v_mad_i64_i32 v[48:49], s[26:27], v48, s11, v[140:141]
	v_lshl_add_u64 v[48:49], v[48:49], 0, v[142:143]
	v_cvt_pk_bf16_f32 v40, v40, v41
	v_cvt_pk_bf16_f32 v41, v42, v43
	v_cvt_pk_bf16_f32 v42, v32, v33
	v_cvt_pk_bf16_f32 v43, v34, v35
	global_store_dwordx4 v[48:49], v[40:43], off
	v_pk_mul_f32 v[24:25], v[28:29], v[24:25]
	v_pk_mul_f32 v[26:27], v[30:31], v[26:27]
	v_pk_mul_f32 v[16:17], v[20:21], v[16:17]
	v_pk_mul_f32 v[18:19], v[22:23], v[18:19]
	v_pk_mul_f32 v[28:29], v[28:29], s[98:99] op_sel_hi:[1,0]
	v_pk_mul_f32 v[30:31], v[30:31], s[98:99] op_sel_hi:[1,0]
	v_pk_mul_f32 v[20:21], v[20:21], s[98:99] op_sel_hi:[1,0]
	v_pk_mul_f32 v[22:23], v[22:23], s[98:99] op_sel_hi:[1,0]
	v_exp_f32_e32 v28, v28
	v_exp_f32_e32 v29, v29
	v_exp_f32_e32 v30, v30
	v_exp_f32_e32 v31, v31
	v_exp_f32_e32 v20, v20
	v_exp_f32_e32 v21, v21
	v_exp_f32_e32 v22, v22
	v_exp_f32_e32 v23, v23
	v_pk_add_f32 v[28:29], v[28:29], s[98:99] op_sel:[0,1]
	v_pk_add_f32 v[30:31], v[30:31], s[98:99] op_sel:[0,1]
	v_pk_add_f32 v[20:21], v[20:21], s[98:99] op_sel:[0,1]
	v_pk_add_f32 v[22:23], v[22:23], s[98:99] op_sel:[0,1]
	v_rcp_f32_e32 v28, v28
	v_rcp_f32_e32 v29, v29
	v_rcp_f32_e32 v30, v30
	v_rcp_f32_e32 v31, v31
	v_rcp_f32_e32 v20, v20
	v_rcp_f32_e32 v21, v21
	v_rcp_f32_e32 v22, v22
	v_rcp_f32_e32 v23, v23
	v_pk_mul_f32 v[24:25], v[28:29], v[24:25]
	v_pk_mul_f32 v[26:27], v[30:31], v[26:27]
	v_pk_mul_f32 v[16:17], v[20:21], v[16:17]
	v_pk_mul_f32 v[18:19], v[22:23], v[18:19]
	v_add_u32_e32 v32, 0xa0, v148
	v_mad_i64_i32 v[32:33], s[26:27], v32, s11, v[140:141]
	v_lshl_add_u64 v[32:33], v[32:33], 0, v[142:143]
	v_cvt_pk_bf16_f32 v24, v24, v25
	v_cvt_pk_bf16_f32 v25, v26, v27
	v_cvt_pk_bf16_f32 v26, v16, v17
	v_cvt_pk_bf16_f32 v27, v18, v19
	global_store_dwordx4 v[32:33], v[24:27], off
	v_pk_mul_f32 v[8:9], v[12:13], v[8:9]
	v_pk_mul_f32 v[10:11], v[14:15], v[10:11]
	v_pk_mul_f32 v[0:1], v[4:5], v[0:1]
	v_pk_mul_f32 v[2:3], v[6:7], v[2:3]
	v_pk_mul_f32 v[12:13], v[12:13], s[98:99] op_sel_hi:[1,0]
	v_pk_mul_f32 v[14:15], v[14:15], s[98:99] op_sel_hi:[1,0]
	v_pk_mul_f32 v[4:5], v[4:5], s[98:99] op_sel_hi:[1,0]
	v_pk_mul_f32 v[6:7], v[6:7], s[98:99] op_sel_hi:[1,0]
	v_exp_f32_e32 v12, v12
	v_exp_f32_e32 v13, v13
	v_exp_f32_e32 v14, v14
	v_exp_f32_e32 v15, v15
	v_exp_f32_e32 v4, v4
	v_exp_f32_e32 v5, v5
	v_exp_f32_e32 v6, v6
	v_exp_f32_e32 v7, v7
	v_pk_add_f32 v[12:13], v[12:13], s[98:99] op_sel:[0,1]
	v_pk_add_f32 v[14:15], v[14:15], s[98:99] op_sel:[0,1]
	v_pk_add_f32 v[4:5], v[4:5], s[98:99] op_sel:[0,1]
	v_pk_add_f32 v[6:7], v[6:7], s[98:99] op_sel:[0,1]
	v_rcp_f32_e32 v12, v12
	v_rcp_f32_e32 v13, v13
	v_rcp_f32_e32 v14, v14
	v_rcp_f32_e32 v15, v15
	v_rcp_f32_e32 v4, v4
	v_rcp_f32_e32 v5, v5
	v_rcp_f32_e32 v6, v6
	v_rcp_f32_e32 v7, v7
	v_pk_mul_f32 v[8:9], v[12:13], v[8:9]
	v_pk_mul_f32 v[10:11], v[14:15], v[10:11]
	v_pk_mul_f32 v[0:1], v[4:5], v[0:1]
	v_pk_mul_f32 v[2:3], v[6:7], v[2:3]
	v_add_u32_e32 v16, 0xb0, v148
	v_mad_i64_i32 v[16:17], s[26:27], v16, s11, v[140:141]
	v_lshl_add_u64 v[16:17], v[16:17], 0, v[142:143]
	s_mov_b64 s[36:37], -1
	s_andn2_b64 vcc, exec, s[38:39]
	s_mov_b64 s[30:31], 0x3200000
	s_mov_b32 s34, s74
	v_cvt_pk_bf16_f32 v8, v8, v9
	v_cvt_pk_bf16_f32 v9, v10, v11
	v_cvt_pk_bf16_f32 v10, v0, v1
	v_cvt_pk_bf16_f32 v11, v2, v3
	global_store_dwordx4 v[16:17], v[8:11], off
	s_cbranch_vccnz .LBB0_809
	s_andn2_b64 vcc, exec, s[42:43]
	s_cbranch_vccnz .LBB0_808
	s_barrier
	s_branch .LBB0_808
